# FFN-up epilogue: cross-group DPP movs merged into the in-group shifted value (no bound_ctrl on the second mov), 21 packed adds and 42 movs become 42 movs
# speedup vs baseline: 1.0046x; 1.0046x over previous
; __device__ __forceinline__ unsigned pk2(float lo, float hi) { unsigned r; asm volatile("v_cvt_pk_bf16_f32 %0, %1, %2" : "=v"(r) : "v"(lo), "v"(hi)); return r; }
; template <int CTRL> __device__ __forceinline__ float dppz(float x) { return __builtin_bit_cast(float, __builtin_amdgcn_update_dpp(0, __builtin_bit_cast(int, x), CTRL, 0xf, 0xf, true)); }
;     __device__ __forceinline__ void fast(const f32x4 (&acc)[2][2][4][2], const pg8::Unit& u, int wr, int wc, int fr, int fq, RsCache& rsc) const {
;     ...
;             for (int m = 0; m < 4; ++m) {
;                 const int row = rowb + m * 16 + fr; const float s = rsc.tab[ai * 64 + m * 16 + fr]; const f32x2 s2 = (f32x2){s, s};
;                 f32x2 g[4], o[4], v[4];
; #pragma unroll
;                 for (int cp = 0; cp < 4; ++cp) { const int n = cp >> 1, e0 = (cp & 1) * 2;
;                     g[cp] = (f32x2){acc[ai][0][m][n][e0], acc[ai][0][m][n][e0 + 1]} * s2; v[cp] = (f32x2){acc[ai][1][m][n][e0], acc[ai][1][m][n][e0 + 1]} * s2; }
; #pragma unroll
;                 for (int cp = 0; cp < 4; ++cp) {
;                     f32x2 p1 = (f32x2){dppz<0x111>(g[cp].x), dppz<0x111>(g[cp].y)}, p2 = (f32x2){dppz<0x112>(g[cp].x), dppz<0x112>(g[cp].y)};
;                     if (m > 0) { p1 += (f32x2){dppz<0x10F>(gp[cp].x), dppz<0x10F>(gp[cp].y)}; p2 += (f32x2){dppz<0x10E>(gp[cp].x), dppz<0x10E>(gp[cp].y)}; }
;                     const f32x2 gv = bb[cp] + w0[cp] * p2 + w1[cp] * p1 + w2[cp] * g[cp];
;                     const f32x2 ea = gv * (-1.44269504089f);
;                     f32x2 ex; ex.x = __builtin_amdgcn_exp2f(ea.x); ex.y = __builtin_amdgcn_exp2f(ea.y);
;                     const f32x2 dn = ex + 1.0f;
;                     f32x2 rc; rc.x = __builtin_amdgcn_rcpf(dn.x); rc.y = __builtin_amdgcn_rcpf(dn.y);
;                     o[cp] = (gv * rc) * v[cp];
;                 }
;                 if (m > 0 || fr >= 2) { uint4 w; w.x = pk2(o[0].x, o[0].y); w.y = pk2(o[1].x, o[1].y); w.z = pk2(o[2].x, o[2].y); w.w = pk2(o[3].x, o[3].y); *(uint4*)(act + (size_t)row * FH + ch) = w; }
.LBB0_270:
	s_or_b64 exec, exec, s[82:83]
	ds_read_b32 v164, v223 offset:64
	s_mov_b32 s2, 0xbfb8aa3b
	v_readlane_b32 s74, v253, 16
	s_waitcnt lgkmcnt(0)
	v_pk_mul_f32 v[162:163], v[150:151], v[164:165] op_sel_hi:[1,0]
	v_pk_mul_f32 v[168:169], v[142:143], v[164:165] op_sel_hi:[1,0]
	v_pk_mul_f32 v[142:143], v[148:149], v[164:165] op_sel_hi:[1,0]
	v_mov_b32_dpp v148, v162 row_shr:2 row_mask:0xf bank_mask:0xf bound_ctrl:1
	v_mov_b32_dpp v149, v163 row_shr:2 row_mask:0xf bank_mask:0xf bound_ctrl:1
	v_pk_mul_f32 v[150:151], v[152:153], v[164:165] op_sel_hi:[1,0]
	v_pk_mul_f32 v[152:153], v[144:145], v[164:165] op_sel_hi:[1,0]
	v_pk_mul_f32 v[144:145], v[146:147], v[164:165] op_sel_hi:[1,0]
	v_pk_mul_f32 v[138:139], v[138:139], v[164:165] op_sel_hi:[1,0]
	v_pk_mul_f32 v[140:141], v[140:141], v[164:165] op_sel_hi:[1,0]
	v_mov_b32_dpp v146, v162 row_shr:1 row_mask:0xf bank_mask:0xf bound_ctrl:1
	v_mov_b32_dpp v147, v163 row_shr:1 row_mask:0xf bank_mask:0xf bound_ctrl:1
	v_mov_b32_dpp v148, v188 row_shl:14 row_mask:0xf bank_mask:0xf
	v_mov_b32_dpp v149, v189 row_shl:14 row_mask:0xf bank_mask:0xf
	v_mov_b32_dpp v146, v188 row_shl:15 row_mask:0xf bank_mask:0xf
	v_mov_b32_dpp v147, v189 row_shl:15 row_mask:0xf bank_mask:0xf
	s_waitcnt vmcnt(0)
	v_pk_fma_f32 v[148:149], v[90:91], v[148:149], v[102:103]
	v_mov_b32_dpp v164, v150 row_shr:2 row_mask:0xf bank_mask:0xf bound_ctrl:1
	v_pk_fma_f32 v[146:147], v[94:95], v[146:147], v[148:149]
	v_mov_b32_dpp v165, v151 row_shr:2 row_mask:0xf bank_mask:0xf bound_ctrl:1
	v_pk_fma_f32 v[146:147], v[98:99], v[162:163], v[146:147]
	v_readlane_b32 s75, v253, 17
	v_pk_mul_f32 v[148:149], v[146:147], s[2:3] op_sel_hi:[1,0]
	v_cmp_lt_i32_e32 vcc, 13, v186
	v_exp_f32_e32 v148, v148
	v_exp_f32_e32 v149, v149
	v_lshl_add_u64 v[156:157], v[186:187], 0, -12
	v_pk_add_f32 v[148:149], v[148:149], 1.0 op_sel_hi:[1,0]
	s_nop 0
	v_rcp_f32_e32 v148, v148
	v_rcp_f32_e32 v149, v149
	s_nop 0
	v_pk_mul_f32 v[146:147], v[146:147], v[148:149]
	s_nop 0
	v_pk_mul_f32 v[146:147], v[168:169], v[146:147]
	v_mov_b32_dpp v168, v166 row_shl:15 row_mask:0xf bank_mask:0xf bound_ctrl:1
	v_mov_b32_dpp v169, v167 row_shl:15 row_mask:0xf bank_mask:0xf bound_ctrl:1
	v_mov_b32_dpp v148, v150 row_shr:1 row_mask:0xf bank_mask:0xf bound_ctrl:1
	v_mov_b32_dpp v149, v151 row_shr:1 row_mask:0xf bank_mask:0xf bound_ctrl:1
	v_mov_b32_dpp v164, v166 row_shl:14 row_mask:0xf bank_mask:0xf
	v_mov_b32_dpp v165, v167 row_shl:14 row_mask:0xf bank_mask:0xf
	v_pk_add_f32 v[148:149], v[148:149], v[168:169]
	v_pk_fma_f32 v[164:165], v[92:93], v[164:165], v[104:105]
	v_mov_b32_dpp v166, v160 row_shl:15 row_mask:0xf bank_mask:0xf bound_ctrl:1
	v_pk_fma_f32 v[148:149], v[96:97], v[148:149], v[164:165]
	v_mov_b32_dpp v167, v161 row_shl:15 row_mask:0xf bank_mask:0xf bound_ctrl:1
	v_pk_fma_f32 v[148:149], v[100:101], v[150:151], v[148:149]
	v_mov_b32_dpp v160, v160 row_shl:14 row_mask:0xf bank_mask:0xf bound_ctrl:1
	v_pk_mul_f32 v[164:165], v[148:149], s[2:3] op_sel_hi:[1,0]
	v_mov_b32_dpp v161, v161 row_shl:14 row_mask:0xf bank_mask:0xf bound_ctrl:1
	v_exp_f32_e32 v164, v164
	v_exp_f32_e32 v165, v165
	v_cvt_pk_bf16_f32 v146, v146, v147
	s_nop 0
	v_pk_add_f32 v[164:165], v[164:165], 1.0 op_sel_hi:[1,0]
	s_nop 0
	v_rcp_f32_e32 v164, v164
	v_rcp_f32_e32 v165, v165
	s_nop 0
	v_pk_mul_f32 v[148:149], v[148:149], v[164:165]
	v_mov_b32_dpp v164, v144 row_shr:2 row_mask:0xf bank_mask:0xf bound_ctrl:1
	v_mov_b32_dpp v165, v145 row_shr:2 row_mask:0xf bank_mask:0xf bound_ctrl:1
	v_pk_mul_f32 v[148:149], v[152:153], v[148:149]
	v_mov_b32_dpp v152, v144 row_shr:1 row_mask:0xf bank_mask:0xf bound_ctrl:1
	v_mov_b32_dpp v153, v145 row_shr:1 row_mask:0xf bank_mask:0xf bound_ctrl:1
	v_pk_add_f32 v[160:161], v[164:165], v[160:161]
	v_pk_add_f32 v[152:153], v[152:153], v[166:167]
	v_pk_fma_f32 v[160:161], v[70:71], v[160:161], v[74:75]
	v_mov_b32_dpp v164, v158 row_shl:15 row_mask:0xf bank_mask:0xf bound_ctrl:1
	v_pk_fma_f32 v[152:153], v[58:59], v[152:153], v[160:161]
	v_mov_b32_dpp v165, v159 row_shl:15 row_mask:0xf bank_mask:0xf bound_ctrl:1
	v_pk_fma_f32 v[152:153], v[66:67], v[144:145], v[152:153]
	v_mov_b32_dpp v158, v158 row_shl:14 row_mask:0xf bank_mask:0xf bound_ctrl:1
	v_pk_mul_f32 v[160:161], v[152:153], s[2:3] op_sel_hi:[1,0]
	v_mov_b32_dpp v159, v159 row_shl:14 row_mask:0xf bank_mask:0xf bound_ctrl:1
	v_exp_f32_e32 v160, v160
	v_exp_f32_e32 v161, v161
	v_add_u32_e32 v166, 16, v224
	v_cvt_pk_bf16_f32 v147, v148, v149
	v_pk_add_f32 v[160:161], v[160:161], 1.0 op_sel_hi:[1,0]
	s_nop 0
	v_rcp_f32_e32 v160, v160
	v_rcp_f32_e32 v161, v161
	s_nop 0
	v_pk_mul_f32 v[152:153], v[152:153], v[160:161]
	v_mov_b32_dpp v160, v142 row_shr:2 row_mask:0xf bank_mask:0xf bound_ctrl:1
	v_mov_b32_dpp v161, v143 row_shr:2 row_mask:0xf bank_mask:0xf bound_ctrl:1
	v_pk_mul_f32 v[138:139], v[138:139], v[152:153]
	v_mov_b32_dpp v152, v142 row_shr:1 row_mask:0xf bank_mask:0xf bound_ctrl:1
	v_mov_b32_dpp v153, v143 row_shr:1 row_mask:0xf bank_mask:0xf bound_ctrl:1
	v_pk_add_f32 v[158:159], v[160:161], v[158:159]
	v_pk_add_f32 v[152:153], v[152:153], v[164:165]
	v_pk_fma_f32 v[158:159], v[72:73], v[158:159], v[76:77]
	v_cvt_pk_bf16_f32 v148, v138, v139
	v_mov_b64_e32 v[138:139], s[74:75]
	v_pk_fma_f32 v[152:153], v[60:61], v[152:153], v[158:159]
	s_nop 0
	v_pk_fma_f32 v[152:153], v[68:69], v[142:143], v[152:153]
	s_nop 0
	v_pk_mul_f32 v[158:159], v[152:153], s[2:3] op_sel_hi:[1,0]
	s_nop 0
	v_exp_f32_e32 v158, v158
	v_exp_f32_e32 v159, v159
	s_nop 0
	v_pk_add_f32 v[158:159], v[158:159], 1.0 op_sel_hi:[1,0]
	s_nop 0
	v_rcp_f32_e32 v158, v158
	v_rcp_f32_e32 v159, v159
	s_nop 0
	v_pk_mul_f32 v[152:153], v[152:153], v[158:159]
	s_nop 0
	v_pk_mul_f32 v[140:141], v[140:141], v[152:153]
	v_cvt_pk_bf16_f32 v149, v140, v141
	v_mad_i64_i32 v[140:141], s[74:75], v166, s93, v[138:139]
	v_lshl_add_u64 v[140:141], v[140:141], 0, v[154:155]
	global_store_dwordx4 v[140:141], v[146:149], off sc1
	ds_read_b32 v146, v223 offset:128
	s_waitcnt lgkmcnt(0)
; __device__ __forceinline__ unsigned pk2(float lo, float hi) { unsigned r; asm volatile("v_cvt_pk_bf16_f32 %0, %1, %2" : "=v"(r) : "v"(lo), "v"(hi)); return r; }
; template <int CTRL> __device__ __forceinline__ float dppz(float x) { return __builtin_bit_cast(float, __builtin_amdgcn_update_dpp(0, __builtin_bit_cast(int, x), CTRL, 0xf, 0xf, true)); }
;     __device__ __forceinline__ void fast(const f32x4 (&acc)[2][2][4][2], const pg8::Unit& u, int wr, int wc, int fr, int fq, RsCache& rsc) const {
;     ...
;             for (int m = 0; m < 4; ++m) {
;                 const int row = rowb + m * 16 + fr; const float s = rsc.tab[ai * 64 + m * 16 + fr]; const f32x2 s2 = (f32x2){s, s};
;                 f32x2 g[4], o[4], v[4];
; #pragma unroll
;                 for (int cp = 0; cp < 4; ++cp) { const int n = cp >> 1, e0 = (cp & 1) * 2;
;                     g[cp] = (f32x2){acc[ai][0][m][n][e0], acc[ai][0][m][n][e0 + 1]} * s2; v[cp] = (f32x2){acc[ai][1][m][n][e0], acc[ai][1][m][n][e0 + 1]} * s2; }
; #pragma unroll
;                 for (int cp = 0; cp < 4; ++cp) {
;                     f32x2 p1 = (f32x2){dppz<0x111>(g[cp].x), dppz<0x111>(g[cp].y)}, p2 = (f32x2){dppz<0x112>(g[cp].x), dppz<0x112>(g[cp].y)};
;                     if (m > 0) { p1 += (f32x2){dppz<0x10F>(gp[cp].x), dppz<0x10F>(gp[cp].y)}; p2 += (f32x2){dppz<0x10E>(gp[cp].x), dppz<0x10E>(gp[cp].y)}; }
;                     const f32x2 gv = bb[cp] + w0[cp] * p2 + w1[cp] * p1 + w2[cp] * g[cp];
;                     const f32x2 ea = gv * (-1.44269504089f);
;                     f32x2 ex; ex.x = __builtin_amdgcn_exp2f(ea.x); ex.y = __builtin_amdgcn_exp2f(ea.y);
;                     const f32x2 dn = ex + 1.0f;
;                     f32x2 rc; rc.x = __builtin_amdgcn_rcpf(dn.x); rc.y = __builtin_amdgcn_rcpf(dn.y);
;                     o[cp] = (gv * rc) * v[cp];
;                 }
;                 if (m > 0 || fr >= 2) { uint4 w; w.x = pk2(o[0].x, o[0].y); w.y = pk2(o[1].x, o[1].y); w.z = pk2(o[2].x, o[2].y); w.w = pk2(o[3].x, o[3].y); *(uint4*)(act + (size_t)row * FH + ch) = w; }
	v_pk_mul_f32 v[140:141], v[134:135], v[146:147] op_sel_hi:[1,0]
	v_pk_mul_f32 v[134:135], v[136:137], v[146:147] op_sel_hi:[1,0]
	s_nop 0
	v_mov_b32_dpp v136, v140 row_shr:2 row_mask:0xf bank_mask:0xf bound_ctrl:1
	v_mov_b32_dpp v137, v141 row_shr:2 row_mask:0xf bank_mask:0xf bound_ctrl:1
	v_pk_mul_f32 v[148:149], v[126:127], v[146:147] op_sel_hi:[1,0]
	v_pk_mul_f32 v[128:129], v[128:129], v[146:147] op_sel_hi:[1,0]
	v_pk_mul_f32 v[126:127], v[130:131], v[146:147] op_sel_hi:[1,0]
	v_pk_mul_f32 v[130:131], v[122:123], v[146:147] op_sel_hi:[1,0]
	v_pk_mul_f32 v[122:123], v[132:133], v[146:147] op_sel_hi:[1,0]
	v_pk_mul_f32 v[124:125], v[124:125], v[146:147] op_sel_hi:[1,0]
	v_mov_b32_dpp v132, v140 row_shr:1 row_mask:0xf bank_mask:0xf bound_ctrl:1
	v_mov_b32_dpp v133, v141 row_shr:1 row_mask:0xf bank_mask:0xf bound_ctrl:1
	v_mov_b32_dpp v136, v162 row_shl:14 row_mask:0xf bank_mask:0xf
	v_mov_b32_dpp v137, v163 row_shl:14 row_mask:0xf bank_mask:0xf
	v_mov_b32_dpp v132, v162 row_shl:15 row_mask:0xf bank_mask:0xf
	v_mov_b32_dpp v133, v163 row_shl:15 row_mask:0xf bank_mask:0xf
	v_pk_fma_f32 v[136:137], v[90:91], v[136:137], v[102:103]
	v_mov_b32_dpp v146, v134 row_shr:2 row_mask:0xf bank_mask:0xf bound_ctrl:1
	v_pk_fma_f32 v[132:133], v[94:95], v[132:133], v[136:137]
	v_mov_b32_dpp v147, v135 row_shr:2 row_mask:0xf bank_mask:0xf bound_ctrl:1
	v_pk_fma_f32 v[132:133], v[98:99], v[140:141], v[132:133]
	s_nop 0
	v_pk_mul_f32 v[136:137], v[132:133], s[2:3] op_sel_hi:[1,0]
	s_nop 0
	v_exp_f32_e32 v136, v136
	v_exp_f32_e32 v137, v137
	s_nop 0
	v_pk_add_f32 v[136:137], v[136:137], 1.0 op_sel_hi:[1,0]
	s_nop 0
	v_rcp_f32_e32 v136, v136
	v_rcp_f32_e32 v137, v137
	s_nop 0
	v_pk_mul_f32 v[132:133], v[132:133], v[136:137]
	s_nop 0
	v_pk_mul_f32 v[132:133], v[148:149], v[132:133]
	v_mov_b32_dpp v148, v150 row_shl:15 row_mask:0xf bank_mask:0xf bound_ctrl:1
	v_mov_b32_dpp v149, v151 row_shl:15 row_mask:0xf bank_mask:0xf bound_ctrl:1
	v_mov_b32_dpp v136, v134 row_shr:1 row_mask:0xf bank_mask:0xf bound_ctrl:1
	v_mov_b32_dpp v137, v135 row_shr:1 row_mask:0xf bank_mask:0xf bound_ctrl:1
	v_mov_b32_dpp v146, v150 row_shl:14 row_mask:0xf bank_mask:0xf
	v_mov_b32_dpp v147, v151 row_shl:14 row_mask:0xf bank_mask:0xf
	v_pk_add_f32 v[136:137], v[136:137], v[148:149]
	v_pk_fma_f32 v[146:147], v[92:93], v[146:147], v[104:105]
	v_mov_b32_dpp v148, v144 row_shl:15 row_mask:0xf bank_mask:0xf bound_ctrl:1
	v_pk_fma_f32 v[136:137], v[96:97], v[136:137], v[146:147]
	v_mov_b32_dpp v149, v145 row_shl:15 row_mask:0xf bank_mask:0xf bound_ctrl:1
	v_pk_fma_f32 v[136:137], v[100:101], v[134:135], v[136:137]
	v_mov_b32_dpp v144, v144 row_shl:14 row_mask:0xf bank_mask:0xf bound_ctrl:1
	v_pk_mul_f32 v[146:147], v[136:137], s[2:3] op_sel_hi:[1,0]
	v_mov_b32_dpp v145, v145 row_shl:14 row_mask:0xf bank_mask:0xf bound_ctrl:1
	v_exp_f32_e32 v146, v146
	v_exp_f32_e32 v147, v147
	s_nop 0
	v_pk_add_f32 v[146:147], v[146:147], 1.0 op_sel_hi:[1,0]
	s_nop 0
	v_rcp_f32_e32 v146, v146
	v_rcp_f32_e32 v147, v147
	s_nop 0
	v_pk_mul_f32 v[136:137], v[136:137], v[146:147]
	v_mov_b32_dpp v146, v126 row_shr:2 row_mask:0xf bank_mask:0xf bound_ctrl:1
	v_mov_b32_dpp v147, v127 row_shr:2 row_mask:0xf bank_mask:0xf bound_ctrl:1
	v_pk_mul_f32 v[136:137], v[128:129], v[136:137]
	v_mov_b32_dpp v128, v126 row_shr:1 row_mask:0xf bank_mask:0xf bound_ctrl:1
	v_mov_b32_dpp v129, v127 row_shr:1 row_mask:0xf bank_mask:0xf bound_ctrl:1
	v_pk_add_f32 v[144:145], v[146:147], v[144:145]
	v_pk_add_f32 v[128:129], v[128:129], v[148:149]
	v_pk_fma_f32 v[144:145], v[70:71], v[144:145], v[74:75]
	v_mov_b32_dpp v146, v142 row_shl:15 row_mask:0xf bank_mask:0xf bound_ctrl:1
	v_pk_fma_f32 v[128:129], v[58:59], v[128:129], v[144:145]
	v_mov_b32_dpp v147, v143 row_shl:15 row_mask:0xf bank_mask:0xf bound_ctrl:1
	v_pk_fma_f32 v[128:129], v[66:67], v[126:127], v[128:129]
	v_mov_b32_dpp v142, v142 row_shl:14 row_mask:0xf bank_mask:0xf bound_ctrl:1
	v_pk_mul_f32 v[144:145], v[128:129], s[2:3] op_sel_hi:[1,0]
	v_mov_b32_dpp v143, v143 row_shl:14 row_mask:0xf bank_mask:0xf bound_ctrl:1
	v_exp_f32_e32 v144, v144
	v_exp_f32_e32 v145, v145
	v_add_u32_e32 v148, 32, v224
	v_pk_add_f32 v[144:145], v[144:145], 1.0 op_sel_hi:[1,0]
	s_nop 0
	v_rcp_f32_e32 v144, v144
	v_rcp_f32_e32 v145, v145
	s_nop 0
	v_pk_mul_f32 v[128:129], v[128:129], v[144:145]
	v_mov_b32_dpp v144, v122 row_shr:2 row_mask:0xf bank_mask:0xf bound_ctrl:1
	v_mov_b32_dpp v145, v123 row_shr:2 row_mask:0xf bank_mask:0xf bound_ctrl:1
	v_pk_mul_f32 v[130:131], v[130:131], v[128:129]
	v_mov_b32_dpp v128, v122 row_shr:1 row_mask:0xf bank_mask:0xf bound_ctrl:1
	v_mov_b32_dpp v129, v123 row_shr:1 row_mask:0xf bank_mask:0xf bound_ctrl:1
	v_pk_add_f32 v[142:143], v[144:145], v[142:143]
	v_pk_add_f32 v[128:129], v[128:129], v[146:147]
	v_pk_fma_f32 v[142:143], v[72:73], v[142:143], v[76:77]
	s_nop 0
	v_pk_fma_f32 v[128:129], v[60:61], v[128:129], v[142:143]
	s_nop 0
	v_pk_fma_f32 v[128:129], v[68:69], v[122:123], v[128:129]
	s_nop 0
	v_pk_mul_f32 v[142:143], v[128:129], s[2:3] op_sel_hi:[1,0]
	s_nop 0
	v_exp_f32_e32 v142, v142
	v_exp_f32_e32 v143, v143
	s_nop 0
	v_pk_add_f32 v[142:143], v[142:143], 1.0 op_sel_hi:[1,0]
	s_nop 0
	v_rcp_f32_e32 v142, v142
	v_rcp_f32_e32 v143, v143
	s_nop 0
	v_pk_mul_f32 v[128:129], v[128:129], v[142:143]
	s_nop 0
	v_pk_mul_f32 v[124:125], v[124:125], v[128:129]
	v_cvt_pk_bf16_f32 v128, v132, v133
	v_cvt_pk_bf16_f32 v129, v136, v137
	v_cvt_pk_bf16_f32 v130, v130, v131
	v_cvt_pk_bf16_f32 v131, v124, v125
	v_mad_i64_i32 v[124:125], s[74:75], v148, s93, v[138:139]
	v_lshl_add_u64 v[124:125], v[124:125], 0, v[154:155]
	global_store_dwordx4 v[124:125], v[128:131], off sc1
	ds_read_b32 v124, v223 offset:192
	s_waitcnt lgkmcnt(0)
;     __device__ __forceinline__ void fast(const f32x4 (&acc)[2][2][4][2], const pg8::Unit& u, int wr, int wc, int fr, int fq, RsCache& rsc) const {
;     ...
;             for (int m = 0; m < 4; ++m) {
;                 const int row = rowb + m * 16 + fr; const float s = rsc.tab[ai * 64 + m * 16 + fr]; const f32x2 s2 = (f32x2){s, s};
;                 f32x2 g[4], o[4], v[4];
; #pragma unroll
;                 for (int cp = 0; cp < 4; ++cp) { const int n = cp >> 1, e0 = (cp & 1) * 2;
;                     g[cp] = (f32x2){acc[ai][0][m][n][e0], acc[ai][0][m][n][e0 + 1]} * s2; v[cp] = (f32x2){acc[ai][1][m][n][e0], acc[ai][1][m][n][e0 + 1]} * s2; }
; #pragma unroll
;                 for (int cp = 0; cp < 4; ++cp) {
;                     f32x2 p1 = (f32x2){dppz<0x111>(g[cp].x), dppz<0x111>(g[cp].y)}, p2 = (f32x2){dppz<0x112>(g[cp].x), dppz<0x112>(g[cp].y)};
;                     if (m > 0) { p1 += (f32x2){dppz<0x10F>(gp[cp].x), dppz<0x10F>(gp[cp].y)}; p2 += (f32x2){dppz<0x10E>(gp[cp].x), dppz<0x10E>(gp[cp].y)}; }
;                     const f32x2 gv = bb[cp] + w0[cp] * p2 + w1[cp] * p1 + w2[cp] * g[cp];
;                     const f32x2 ea = gv * (-1.44269504089f);
;                     f32x2 ex; ex.x = __builtin_amdgcn_exp2f(ea.x); ex.y = __builtin_amdgcn_exp2f(ea.y);
;                     const f32x2 dn = ex + 1.0f;
;                     f32x2 rc; rc.x = __builtin_amdgcn_rcpf(dn.x); rc.y = __builtin_amdgcn_rcpf(dn.y);
;                     o[cp] = (gv * rc) * v[cp];
;                 }
;                 if (m > 0 || fr >= 2) { uint4 w; w.x = pk2(o[0].x, o[0].y); w.y = pk2(o[1].x, o[1].y); w.z = pk2(o[2].x, o[2].y); w.w = pk2(o[3].x, o[3].y); *(uint4*)(act + (size_t)row * FH + ch) = w; }
;                 if (m == 0 && fr < 2) { uint4 w; w.x = pk2(g[0].x, g[0].y); w.y = pk2(g[1].x, g[1].y); w.z = pk2(g[2].x, g[2].y); w.w = pk2(g[3].x, g[3].y); *(uint4*)(sideg + ((size_t)blk * 4 + fr) * FH + ch) = w;
;                     uint4 q; q.x = pk2(v[0].x, v[0].y); q.y = pk2(v[1].x, v[1].y); q.z = pk2(v[2].x, v[2].y); q.w = pk2(v[3].x, v[3].y); *(uint4*)(sidev + ((size_t)blk * 2 + fr) * FH + ch) = q; }
;                 if (m == 3 && fr >= 14) { uint4 w; w.x = pk2(g[0].x, g[0].y); w.y = pk2(g[1].x, g[1].y); w.z = pk2(g[2].x, g[2].y); w.w = pk2(g[3].x, g[3].y); *(uint4*)(sideg + ((size_t)blk * 4 + 2 + (fr - 14)) * FH + ch) = w; }
	v_pk_mul_f32 v[118:119], v[118:119], v[124:125] op_sel_hi:[1,0]
	v_pk_mul_f32 v[128:129], v[110:111], v[124:125] op_sel_hi:[1,0]
	v_pk_mul_f32 v[110:111], v[120:121], v[124:125] op_sel_hi:[1,0]
	v_pk_mul_f32 v[120:121], v[112:113], v[124:125] op_sel_hi:[1,0]
	v_pk_mul_f32 v[112:113], v[114:115], v[124:125] op_sel_hi:[1,0]
	v_pk_mul_f32 v[114:115], v[106:107], v[124:125] op_sel_hi:[1,0]
	v_pk_mul_f32 v[106:107], v[116:117], v[124:125] op_sel_hi:[1,0]
	v_pk_mul_f32 v[108:109], v[108:109], v[124:125] op_sel_hi:[1,0]
	v_mov_b32_dpp v124, v118 row_shr:2 row_mask:0xf bank_mask:0xf bound_ctrl:1
	v_mov_b32_dpp v125, v119 row_shr:2 row_mask:0xf bank_mask:0xf bound_ctrl:1
	v_mov_b32_dpp v116, v118 row_shr:1 row_mask:0xf bank_mask:0xf bound_ctrl:1
	v_mov_b32_dpp v117, v119 row_shr:1 row_mask:0xf bank_mask:0xf bound_ctrl:1
	v_mov_b32_dpp v124, v140 row_shl:14 row_mask:0xf bank_mask:0xf
	v_mov_b32_dpp v125, v141 row_shl:14 row_mask:0xf bank_mask:0xf
	v_mov_b32_dpp v116, v140 row_shl:15 row_mask:0xf bank_mask:0xf
	v_mov_b32_dpp v117, v141 row_shl:15 row_mask:0xf bank_mask:0xf
	v_pk_fma_f32 v[124:125], v[90:91], v[124:125], v[102:103]
	v_pk_fma_f32 v[116:117], v[94:95], v[116:117], v[124:125]
	v_pk_fma_f32 v[116:117], v[98:99], v[118:119], v[116:117]
	v_pk_mul_f32 v[124:125], v[116:117], s[2:3] op_sel_hi:[1,0]
	v_exp_f32_e32 v124, v124
	v_exp_f32_e32 v125, v125
	s_nop 0
	v_pk_add_f32 v[124:125], v[124:125], 1.0 op_sel_hi:[1,0]
	s_nop 0
	v_rcp_f32_e32 v124, v124
	v_rcp_f32_e32 v125, v125
	s_nop 0
	v_pk_mul_f32 v[116:117], v[116:117], v[124:125]
	s_nop 0
	v_pk_mul_f32 v[116:117], v[128:129], v[116:117]
	v_mov_b32_dpp v128, v110 row_shr:2 row_mask:0xf bank_mask:0xf bound_ctrl:1
	v_mov_b32_dpp v129, v111 row_shr:2 row_mask:0xf bank_mask:0xf bound_ctrl:1
	v_mov_b32_dpp v124, v110 row_shr:1 row_mask:0xf bank_mask:0xf bound_ctrl:1
	v_mov_b32_dpp v125, v111 row_shr:1 row_mask:0xf bank_mask:0xf bound_ctrl:1
	v_mov_b32_dpp v128, v134 row_shl:14 row_mask:0xf bank_mask:0xf
	v_mov_b32_dpp v129, v135 row_shl:14 row_mask:0xf bank_mask:0xf
	v_mov_b32_dpp v124, v134 row_shl:15 row_mask:0xf bank_mask:0xf
	v_mov_b32_dpp v125, v135 row_shl:15 row_mask:0xf bank_mask:0xf
	v_pk_fma_f32 v[128:129], v[92:93], v[128:129], v[104:105]
	v_mov_b32_dpp v130, v126 row_shl:15 row_mask:0xf bank_mask:0xf bound_ctrl:1
	v_pk_fma_f32 v[124:125], v[96:97], v[124:125], v[128:129]
	v_mov_b32_dpp v131, v127 row_shl:15 row_mask:0xf bank_mask:0xf bound_ctrl:1
	v_pk_fma_f32 v[124:125], v[100:101], v[110:111], v[124:125]
	v_mov_b32_dpp v126, v126 row_shl:14 row_mask:0xf bank_mask:0xf bound_ctrl:1
	v_pk_mul_f32 v[128:129], v[124:125], s[2:3] op_sel_hi:[1,0]
	v_mov_b32_dpp v127, v127 row_shl:14 row_mask:0xf bank_mask:0xf bound_ctrl:1
	v_exp_f32_e32 v128, v128
	v_exp_f32_e32 v129, v129
	s_nop 0
	v_pk_add_f32 v[128:129], v[128:129], 1.0 op_sel_hi:[1,0]
	s_nop 0
	v_rcp_f32_e32 v128, v128
	v_rcp_f32_e32 v129, v129
	s_nop 0
	v_pk_mul_f32 v[124:125], v[124:125], v[128:129]
	v_mov_b32_dpp v128, v112 row_shr:2 row_mask:0xf bank_mask:0xf bound_ctrl:1
	v_mov_b32_dpp v129, v113 row_shr:2 row_mask:0xf bank_mask:0xf bound_ctrl:1
	v_pk_mul_f32 v[120:121], v[120:121], v[124:125]
	v_mov_b32_dpp v124, v112 row_shr:1 row_mask:0xf bank_mask:0xf bound_ctrl:1
	v_mov_b32_dpp v125, v113 row_shr:1 row_mask:0xf bank_mask:0xf bound_ctrl:1
	v_pk_add_f32 v[126:127], v[128:129], v[126:127]
	v_pk_add_f32 v[124:125], v[124:125], v[130:131]
	v_pk_fma_f32 v[126:127], v[70:71], v[126:127], v[74:75]
	v_mov_b32_dpp v128, v122 row_shl:15 row_mask:0xf bank_mask:0xf bound_ctrl:1
	v_pk_fma_f32 v[124:125], v[58:59], v[124:125], v[126:127]
	v_mov_b32_dpp v129, v123 row_shl:15 row_mask:0xf bank_mask:0xf bound_ctrl:1
	v_pk_fma_f32 v[124:125], v[66:67], v[112:113], v[124:125]
	v_mov_b32_dpp v122, v122 row_shl:14 row_mask:0xf bank_mask:0xf bound_ctrl:1
	v_pk_mul_f32 v[126:127], v[124:125], s[2:3] op_sel_hi:[1,0]
	v_mov_b32_dpp v123, v123 row_shl:14 row_mask:0xf bank_mask:0xf bound_ctrl:1
	v_exp_f32_e32 v126, v126
	v_exp_f32_e32 v127, v127
	v_add_u32_e32 v130, 48, v224
	v_pk_add_f32 v[126:127], v[126:127], 1.0 op_sel_hi:[1,0]
	s_nop 0
	v_rcp_f32_e32 v126, v126
	v_rcp_f32_e32 v127, v127
	s_nop 0
	v_pk_mul_f32 v[124:125], v[124:125], v[126:127]
	v_mov_b32_dpp v126, v106 row_shr:2 row_mask:0xf bank_mask:0xf bound_ctrl:1
	v_mov_b32_dpp v127, v107 row_shr:2 row_mask:0xf bank_mask:0xf bound_ctrl:1
	v_pk_mul_f32 v[124:125], v[114:115], v[124:125]
	v_mov_b32_dpp v114, v106 row_shr:1 row_mask:0xf bank_mask:0xf bound_ctrl:1
	v_mov_b32_dpp v115, v107 row_shr:1 row_mask:0xf bank_mask:0xf bound_ctrl:1
	v_pk_add_f32 v[122:123], v[126:127], v[122:123]
	v_pk_add_f32 v[114:115], v[114:115], v[128:129]
	v_pk_fma_f32 v[122:123], v[72:73], v[122:123], v[76:77]
	s_nop 0
	v_pk_fma_f32 v[114:115], v[60:61], v[114:115], v[122:123]
	s_nop 0
	v_pk_fma_f32 v[114:115], v[68:69], v[106:107], v[114:115]
	s_nop 0
	v_pk_mul_f32 v[122:123], v[114:115], s[2:3] op_sel_hi:[1,0]
	s_nop 0
	v_exp_f32_e32 v122, v122
	v_exp_f32_e32 v123, v123
	s_nop 0
	v_pk_add_f32 v[122:123], v[122:123], 1.0 op_sel_hi:[1,0]
	s_nop 0
	v_rcp_f32_e32 v122, v122
	v_rcp_f32_e32 v123, v123
	s_nop 0
	v_pk_mul_f32 v[114:115], v[114:115], v[122:123]
	s_nop 0
	v_pk_mul_f32 v[108:109], v[108:109], v[114:115]
	v_cvt_pk_bf16_f32 v114, v116, v117
	v_cvt_pk_bf16_f32 v115, v120, v121
	v_cvt_pk_bf16_f32 v116, v124, v125
	s_nop 0
	v_cvt_pk_bf16_f32 v117, v108, v109
	v_mad_i64_i32 v[108:109], s[74:75], v130, s93, v[138:139]
	v_lshl_add_u64 v[108:109], v[108:109], 0, v[154:155]
	global_store_dwordx4 v[108:109], v[114:117], off sc1
	s_and_saveexec_b64 s[82:83], vcc
	s_cbranch_execz .LBB0_272
	v_lshl_add_u64 v[114:115], s[0:1], 0, v[156:157]
	v_readlane_b32 s0, v254, 1
	v_readlane_b32 s1, v254, 2
	v_cvt_pk_bf16_f32 v108, v118, v119
	v_cvt_pk_bf16_f32 v109, v110, v111
	v_cvt_pk_bf16_f32 v110, v112, v113
	v_cvt_pk_bf16_f32 v111, v106, v107
	s_nop 1
	v_mov_b64_e32 v[106:107], s[0:1]
	v_mad_u64_u32 v[106:107], s[0:1], v114, s93, v[106:107]
	v_mad_i32_i24 v107, v115, s93, v107
	v_lshl_add_u64 v[106:107], v[184:185], 1, v[106:107]
	global_store_dwordx4 v[106:107], v[108:111], off sc1

; __device__ __forceinline__ unsigned pk2(float lo, float hi) { unsigned r; asm volatile("v_cvt_pk_bf16_f32 %0, %1, %2" : "=v"(r) : "v"(lo), "v"(hi)); return r; }
; template <int CTRL> __device__ __forceinline__ float dppz(float x) { return __builtin_bit_cast(float, __builtin_amdgcn_update_dpp(0, __builtin_bit_cast(int, x), CTRL, 0xf, 0xf, true)); }
;     __device__ __forceinline__ void fast(const f32x4 (&acc)[2][2][4][2], const pg8::Unit& u, int wr, int wc, int fr, int fq, RsCache& rsc) const {
;     ...
;             for (int m = 0; m < 4; ++m) {
;                 const int row = rowb + m * 16 + fr; const float s = rsc.tab[ai * 64 + m * 16 + fr]; const f32x2 s2 = (f32x2){s, s};
;                 f32x2 g[4], o[4], v[4];
; #pragma unroll
;                 for (int cp = 0; cp < 4; ++cp) { const int n = cp >> 1, e0 = (cp & 1) * 2;
;                     g[cp] = (f32x2){acc[ai][0][m][n][e0], acc[ai][0][m][n][e0 + 1]} * s2; v[cp] = (f32x2){acc[ai][1][m][n][e0], acc[ai][1][m][n][e0 + 1]} * s2; }
; #pragma unroll
;                 for (int cp = 0; cp < 4; ++cp) {
;                     f32x2 p1 = (f32x2){dppz<0x111>(g[cp].x), dppz<0x111>(g[cp].y)}, p2 = (f32x2){dppz<0x112>(g[cp].x), dppz<0x112>(g[cp].y)};
;                     if (m > 0) { p1 += (f32x2){dppz<0x10F>(gp[cp].x), dppz<0x10F>(gp[cp].y)}; p2 += (f32x2){dppz<0x10E>(gp[cp].x), dppz<0x10E>(gp[cp].y)}; }
;                     const f32x2 gv = bb[cp] + w0[cp] * p2 + w1[cp] * p1 + w2[cp] * g[cp];
;                     const f32x2 ea = gv * (-1.44269504089f);
;                     f32x2 ex; ex.x = __builtin_amdgcn_exp2f(ea.x); ex.y = __builtin_amdgcn_exp2f(ea.y);
;                     const f32x2 dn = ex + 1.0f;
;                     f32x2 rc; rc.x = __builtin_amdgcn_rcpf(dn.x); rc.y = __builtin_amdgcn_rcpf(dn.y);
;                     o[cp] = (gv * rc) * v[cp];
;                 }
;                 if (m > 0 || fr >= 2) { uint4 w; w.x = pk2(o[0].x, o[0].y); w.y = pk2(o[1].x, o[1].y); w.z = pk2(o[2].x, o[2].y); w.w = pk2(o[3].x, o[3].y); *(uint4*)(act + (size_t)row * FH + ch) = w; }
.LBB0_276:
	s_or_b64 exec, exec, s[82:83]
	ds_read_b32 v80, v223 offset:320
	s_mov_b32 s2, 0xbfb8aa3b
	v_readlane_b32 s0, v253, 16
	s_waitcnt lgkmcnt(0)
	v_pk_mul_f32 v[64:65], v[54:55], v[80:81] op_sel_hi:[1,0]
	v_pk_mul_f32 v[82:83], v[46:47], v[80:81] op_sel_hi:[1,0]
	v_pk_mul_f32 v[46:47], v[52:53], v[80:81] op_sel_hi:[1,0]
	v_mov_b32_dpp v52, v64 row_shr:2 row_mask:0xf bank_mask:0xf bound_ctrl:1
	v_mov_b32_dpp v53, v65 row_shr:2 row_mask:0xf bank_mask:0xf bound_ctrl:1
	v_pk_mul_f32 v[54:55], v[56:57], v[80:81] op_sel_hi:[1,0]
	v_pk_mul_f32 v[56:57], v[48:49], v[80:81] op_sel_hi:[1,0]
	v_pk_mul_f32 v[48:49], v[50:51], v[80:81] op_sel_hi:[1,0]
	v_pk_mul_f32 v[42:43], v[42:43], v[80:81] op_sel_hi:[1,0]
	v_pk_mul_f32 v[44:45], v[44:45], v[80:81] op_sel_hi:[1,0]
	v_mov_b32_dpp v50, v64 row_shr:1 row_mask:0xf bank_mask:0xf bound_ctrl:1
	v_mov_b32_dpp v51, v65 row_shr:1 row_mask:0xf bank_mask:0xf bound_ctrl:1
	v_mov_b32_dpp v52, v106 row_shl:14 row_mask:0xf bank_mask:0xf
	v_mov_b32_dpp v53, v107 row_shl:14 row_mask:0xf bank_mask:0xf
	v_mov_b32_dpp v50, v106 row_shl:15 row_mask:0xf bank_mask:0xf
	v_mov_b32_dpp v51, v107 row_shl:15 row_mask:0xf bank_mask:0xf
	v_pk_fma_f32 v[52:53], v[90:91], v[52:53], v[102:103]
	v_mov_b32_dpp v80, v54 row_shr:2 row_mask:0xf bank_mask:0xf bound_ctrl:1
	v_pk_fma_f32 v[50:51], v[94:95], v[50:51], v[52:53]
	v_mov_b32_dpp v81, v55 row_shr:2 row_mask:0xf bank_mask:0xf bound_ctrl:1
	v_pk_fma_f32 v[50:51], v[98:99], v[64:65], v[50:51]
	v_pk_mul_f32 v[52:53], v[50:51], s[2:3] op_sel_hi:[1,0]
	v_exp_f32_e32 v52, v52
	v_exp_f32_e32 v53, v53
	v_mov_b32_dpp v80, v86 row_shl:14 row_mask:0xf bank_mask:0xf
	v_mov_b32_dpp v81, v87 row_shl:14 row_mask:0xf bank_mask:0xf
	v_readlane_b32 s1, v253, 17
	v_pk_fma_f32 v[80:81], v[92:93], v[80:81], v[104:105]
	v_pk_add_f32 v[52:53], v[52:53], 1.0 op_sel_hi:[1,0]
	s_nop 0
	v_rcp_f32_e32 v52, v52
	v_rcp_f32_e32 v53, v53
	s_nop 0
	v_pk_mul_f32 v[50:51], v[50:51], v[52:53]
	s_nop 0
	v_pk_mul_f32 v[50:51], v[82:83], v[50:51]
	v_mov_b32_dpp v52, v54 row_shr:1 row_mask:0xf bank_mask:0xf bound_ctrl:1
	v_mov_b32_dpp v53, v55 row_shr:1 row_mask:0xf bank_mask:0xf bound_ctrl:1
	v_mov_b32_dpp v52, v86 row_shl:15 row_mask:0xf bank_mask:0xf
	v_mov_b32_dpp v53, v87 row_shl:15 row_mask:0xf bank_mask:0xf
	v_mov_b32_dpp v82, v78 row_shl:15 row_mask:0xf bank_mask:0xf bound_ctrl:1
	v_pk_fma_f32 v[52:53], v[96:97], v[52:53], v[80:81]
	v_mov_b32_dpp v83, v79 row_shl:15 row_mask:0xf bank_mask:0xf bound_ctrl:1
	v_pk_fma_f32 v[52:53], v[100:101], v[54:55], v[52:53]
	v_mov_b32_dpp v78, v78 row_shl:14 row_mask:0xf bank_mask:0xf bound_ctrl:1
	v_pk_mul_f32 v[80:81], v[52:53], s[2:3] op_sel_hi:[1,0]
	v_mov_b32_dpp v79, v79 row_shl:14 row_mask:0xf bank_mask:0xf bound_ctrl:1
	v_exp_f32_e32 v80, v80
	v_exp_f32_e32 v81, v81
	v_cvt_pk_bf16_f32 v50, v50, v51
	s_nop 0
	v_pk_add_f32 v[80:81], v[80:81], 1.0 op_sel_hi:[1,0]
	s_nop 0
	v_rcp_f32_e32 v80, v80
	v_rcp_f32_e32 v81, v81
	s_nop 0
	v_pk_mul_f32 v[52:53], v[52:53], v[80:81]
	v_mov_b32_dpp v80, v48 row_shr:2 row_mask:0xf bank_mask:0xf bound_ctrl:1
	v_mov_b32_dpp v81, v49 row_shr:2 row_mask:0xf bank_mask:0xf bound_ctrl:1
	v_pk_mul_f32 v[52:53], v[56:57], v[52:53]
	v_mov_b32_dpp v56, v48 row_shr:1 row_mask:0xf bank_mask:0xf bound_ctrl:1
	v_mov_b32_dpp v57, v49 row_shr:1 row_mask:0xf bank_mask:0xf bound_ctrl:1
	v_pk_add_f32 v[78:79], v[80:81], v[78:79]
	v_pk_add_f32 v[56:57], v[56:57], v[82:83]
	v_pk_fma_f32 v[78:79], v[70:71], v[78:79], v[74:75]
	v_mov_b32_dpp v80, v62 row_shl:15 row_mask:0xf bank_mask:0xf bound_ctrl:1
	v_pk_fma_f32 v[56:57], v[58:59], v[56:57], v[78:79]
	v_mov_b32_dpp v81, v63 row_shl:15 row_mask:0xf bank_mask:0xf bound_ctrl:1
	v_pk_fma_f32 v[56:57], v[66:67], v[48:49], v[56:57]
	v_mov_b32_dpp v62, v62 row_shl:14 row_mask:0xf bank_mask:0xf bound_ctrl:1
	v_pk_mul_f32 v[78:79], v[56:57], s[2:3] op_sel_hi:[1,0]
	v_mov_b32_dpp v63, v63 row_shl:14 row_mask:0xf bank_mask:0xf bound_ctrl:1
	v_exp_f32_e32 v78, v78
	v_exp_f32_e32 v79, v79
	v_add_u32_e32 v82, 16, v122
	v_cvt_pk_bf16_f32 v51, v52, v53
	v_pk_add_f32 v[78:79], v[78:79], 1.0 op_sel_hi:[1,0]
	s_nop 0
	v_rcp_f32_e32 v78, v78
	v_rcp_f32_e32 v79, v79
	s_nop 0
	v_pk_mul_f32 v[56:57], v[56:57], v[78:79]
	v_mov_b32_dpp v78, v46 row_shr:2 row_mask:0xf bank_mask:0xf bound_ctrl:1
	v_mov_b32_dpp v79, v47 row_shr:2 row_mask:0xf bank_mask:0xf bound_ctrl:1
	v_pk_mul_f32 v[42:43], v[42:43], v[56:57]
	v_mov_b32_dpp v56, v46 row_shr:1 row_mask:0xf bank_mask:0xf bound_ctrl:1
	v_mov_b32_dpp v57, v47 row_shr:1 row_mask:0xf bank_mask:0xf bound_ctrl:1
	v_pk_add_f32 v[62:63], v[78:79], v[62:63]
	v_pk_add_f32 v[56:57], v[56:57], v[80:81]
	v_pk_fma_f32 v[62:63], v[72:73], v[62:63], v[76:77]
	v_cvt_pk_bf16_f32 v52, v42, v43
	v_mov_b64_e32 v[42:43], s[0:1]
	v_pk_fma_f32 v[56:57], v[60:61], v[56:57], v[62:63]
	s_nop 0
	v_pk_fma_f32 v[56:57], v[68:69], v[46:47], v[56:57]
	s_nop 0
	v_pk_mul_f32 v[62:63], v[56:57], s[2:3] op_sel_hi:[1,0]
	s_nop 0
	v_exp_f32_e32 v62, v62
	v_exp_f32_e32 v63, v63
	s_nop 0
	v_pk_add_f32 v[62:63], v[62:63], 1.0 op_sel_hi:[1,0]
	s_nop 0
	v_rcp_f32_e32 v62, v62
	v_rcp_f32_e32 v63, v63
	s_nop 0
	v_pk_mul_f32 v[56:57], v[56:57], v[62:63]
	s_nop 0
	v_pk_mul_f32 v[44:45], v[44:45], v[56:57]
	v_cvt_pk_bf16_f32 v53, v44, v45
	v_mad_i64_i32 v[44:45], s[0:1], v82, s93, v[42:43]
	v_lshl_add_u64 v[44:45], v[44:45], 0, v[154:155]
	global_store_dwordx4 v[44:45], v[50:53], off sc1
	ds_read_b32 v50, v223 offset:384
	s_waitcnt lgkmcnt(0)
; __device__ __forceinline__ unsigned pk2(float lo, float hi) { unsigned r; asm volatile("v_cvt_pk_bf16_f32 %0, %1, %2" : "=v"(r) : "v"(lo), "v"(hi)); return r; }
; template <int CTRL> __device__ __forceinline__ float dppz(float x) { return __builtin_bit_cast(float, __builtin_amdgcn_update_dpp(0, __builtin_bit_cast(int, x), CTRL, 0xf, 0xf, true)); }
;     __device__ __forceinline__ void fast(const f32x4 (&acc)[2][2][4][2], const pg8::Unit& u, int wr, int wc, int fr, int fq, RsCache& rsc) const {
;     ...
;             for (int m = 0; m < 4; ++m) {
;                 const int row = rowb + m * 16 + fr; const float s = rsc.tab[ai * 64 + m * 16 + fr]; const f32x2 s2 = (f32x2){s, s};
;                 f32x2 g[4], o[4], v[4];
; #pragma unroll
;                 for (int cp = 0; cp < 4; ++cp) { const int n = cp >> 1, e0 = (cp & 1) * 2;
;                     g[cp] = (f32x2){acc[ai][0][m][n][e0], acc[ai][0][m][n][e0 + 1]} * s2; v[cp] = (f32x2){acc[ai][1][m][n][e0], acc[ai][1][m][n][e0 + 1]} * s2; }
; #pragma unroll
;                 for (int cp = 0; cp < 4; ++cp) {
;                     f32x2 p1 = (f32x2){dppz<0x111>(g[cp].x), dppz<0x111>(g[cp].y)}, p2 = (f32x2){dppz<0x112>(g[cp].x), dppz<0x112>(g[cp].y)};
;                     if (m > 0) { p1 += (f32x2){dppz<0x10F>(gp[cp].x), dppz<0x10F>(gp[cp].y)}; p2 += (f32x2){dppz<0x10E>(gp[cp].x), dppz<0x10E>(gp[cp].y)}; }
;                     const f32x2 gv = bb[cp] + w0[cp] * p2 + w1[cp] * p1 + w2[cp] * g[cp];
;                     const f32x2 ea = gv * (-1.44269504089f);
;                     f32x2 ex; ex.x = __builtin_amdgcn_exp2f(ea.x); ex.y = __builtin_amdgcn_exp2f(ea.y);
;                     const f32x2 dn = ex + 1.0f;
;                     f32x2 rc; rc.x = __builtin_amdgcn_rcpf(dn.x); rc.y = __builtin_amdgcn_rcpf(dn.y);
;                     o[cp] = (gv * rc) * v[cp];
;                 }
;                 if (m > 0 || fr >= 2) { uint4 w; w.x = pk2(o[0].x, o[0].y); w.y = pk2(o[1].x, o[1].y); w.z = pk2(o[2].x, o[2].y); w.w = pk2(o[3].x, o[3].y); *(uint4*)(act + (size_t)row * FH + ch) = w; }
	v_pk_mul_f32 v[44:45], v[38:39], v[50:51] op_sel_hi:[1,0]
	v_pk_mul_f32 v[38:39], v[40:41], v[50:51] op_sel_hi:[1,0]
	s_nop 0
	v_mov_b32_dpp v40, v44 row_shr:2 row_mask:0xf bank_mask:0xf bound_ctrl:1
	v_mov_b32_dpp v41, v45 row_shr:2 row_mask:0xf bank_mask:0xf bound_ctrl:1
	v_pk_mul_f32 v[52:53], v[30:31], v[50:51] op_sel_hi:[1,0]
	v_pk_mul_f32 v[32:33], v[32:33], v[50:51] op_sel_hi:[1,0]
	v_pk_mul_f32 v[30:31], v[34:35], v[50:51] op_sel_hi:[1,0]
	v_pk_mul_f32 v[34:35], v[26:27], v[50:51] op_sel_hi:[1,0]
	v_pk_mul_f32 v[26:27], v[36:37], v[50:51] op_sel_hi:[1,0]
	v_pk_mul_f32 v[28:29], v[28:29], v[50:51] op_sel_hi:[1,0]
	v_mov_b32_dpp v36, v44 row_shr:1 row_mask:0xf bank_mask:0xf bound_ctrl:1
	v_mov_b32_dpp v37, v45 row_shr:1 row_mask:0xf bank_mask:0xf bound_ctrl:1
	v_mov_b32_dpp v40, v64 row_shl:14 row_mask:0xf bank_mask:0xf
	v_mov_b32_dpp v41, v65 row_shl:14 row_mask:0xf bank_mask:0xf
	v_mov_b32_dpp v36, v64 row_shl:15 row_mask:0xf bank_mask:0xf
	v_mov_b32_dpp v37, v65 row_shl:15 row_mask:0xf bank_mask:0xf
	v_pk_fma_f32 v[40:41], v[90:91], v[40:41], v[102:103]
	v_mov_b32_dpp v50, v38 row_shr:2 row_mask:0xf bank_mask:0xf bound_ctrl:1
	v_pk_fma_f32 v[36:37], v[94:95], v[36:37], v[40:41]
	v_mov_b32_dpp v51, v39 row_shr:2 row_mask:0xf bank_mask:0xf bound_ctrl:1
	v_pk_fma_f32 v[36:37], v[98:99], v[44:45], v[36:37]
	s_nop 0
	v_pk_mul_f32 v[40:41], v[36:37], s[2:3] op_sel_hi:[1,0]
	s_nop 0
	v_exp_f32_e32 v40, v40
	v_exp_f32_e32 v41, v41
	s_nop 0
	v_pk_add_f32 v[40:41], v[40:41], 1.0 op_sel_hi:[1,0]
	s_nop 0
	v_rcp_f32_e32 v40, v40
	v_rcp_f32_e32 v41, v41
	s_nop 0
	v_pk_mul_f32 v[36:37], v[36:37], v[40:41]
	s_nop 0
	v_pk_mul_f32 v[36:37], v[52:53], v[36:37]
	v_mov_b32_dpp v52, v54 row_shl:15 row_mask:0xf bank_mask:0xf bound_ctrl:1
	v_mov_b32_dpp v53, v55 row_shl:15 row_mask:0xf bank_mask:0xf bound_ctrl:1
	v_mov_b32_dpp v40, v38 row_shr:1 row_mask:0xf bank_mask:0xf bound_ctrl:1
	v_mov_b32_dpp v41, v39 row_shr:1 row_mask:0xf bank_mask:0xf bound_ctrl:1
	v_mov_b32_dpp v50, v54 row_shl:14 row_mask:0xf bank_mask:0xf
	v_mov_b32_dpp v51, v55 row_shl:14 row_mask:0xf bank_mask:0xf
	v_pk_add_f32 v[40:41], v[40:41], v[52:53]
	v_pk_fma_f32 v[50:51], v[92:93], v[50:51], v[104:105]
	v_mov_b32_dpp v52, v48 row_shl:15 row_mask:0xf bank_mask:0xf bound_ctrl:1
	v_pk_fma_f32 v[40:41], v[96:97], v[40:41], v[50:51]
	v_mov_b32_dpp v53, v49 row_shl:15 row_mask:0xf bank_mask:0xf bound_ctrl:1
	v_pk_fma_f32 v[40:41], v[100:101], v[38:39], v[40:41]
	v_mov_b32_dpp v48, v48 row_shl:14 row_mask:0xf bank_mask:0xf bound_ctrl:1
	v_pk_mul_f32 v[50:51], v[40:41], s[2:3] op_sel_hi:[1,0]
	v_mov_b32_dpp v49, v49 row_shl:14 row_mask:0xf bank_mask:0xf bound_ctrl:1
	v_exp_f32_e32 v50, v50
	v_exp_f32_e32 v51, v51
	s_nop 0
	v_pk_add_f32 v[50:51], v[50:51], 1.0 op_sel_hi:[1,0]
	s_nop 0
	v_rcp_f32_e32 v50, v50
	v_rcp_f32_e32 v51, v51
	s_nop 0
	v_pk_mul_f32 v[40:41], v[40:41], v[50:51]
	v_mov_b32_dpp v50, v30 row_shr:2 row_mask:0xf bank_mask:0xf bound_ctrl:1
	v_mov_b32_dpp v51, v31 row_shr:2 row_mask:0xf bank_mask:0xf bound_ctrl:1
	v_pk_mul_f32 v[40:41], v[32:33], v[40:41]
	v_mov_b32_dpp v32, v30 row_shr:1 row_mask:0xf bank_mask:0xf bound_ctrl:1
	v_mov_b32_dpp v33, v31 row_shr:1 row_mask:0xf bank_mask:0xf bound_ctrl:1
	v_pk_add_f32 v[48:49], v[50:51], v[48:49]
	v_pk_add_f32 v[32:33], v[32:33], v[52:53]
	v_pk_fma_f32 v[48:49], v[70:71], v[48:49], v[74:75]
	v_mov_b32_dpp v50, v46 row_shl:15 row_mask:0xf bank_mask:0xf bound_ctrl:1
	v_pk_fma_f32 v[32:33], v[58:59], v[32:33], v[48:49]
	v_mov_b32_dpp v51, v47 row_shl:15 row_mask:0xf bank_mask:0xf bound_ctrl:1
	v_pk_fma_f32 v[32:33], v[66:67], v[30:31], v[32:33]
	v_mov_b32_dpp v46, v46 row_shl:14 row_mask:0xf bank_mask:0xf bound_ctrl:1
	v_pk_mul_f32 v[48:49], v[32:33], s[2:3] op_sel_hi:[1,0]
	v_mov_b32_dpp v47, v47 row_shl:14 row_mask:0xf bank_mask:0xf bound_ctrl:1
	v_exp_f32_e32 v48, v48
	v_exp_f32_e32 v49, v49
	v_add_u32_e32 v52, 32, v122
	v_pk_add_f32 v[48:49], v[48:49], 1.0 op_sel_hi:[1,0]
	s_nop 0
	v_rcp_f32_e32 v48, v48
	v_rcp_f32_e32 v49, v49
	s_nop 0
	v_pk_mul_f32 v[32:33], v[32:33], v[48:49]
	v_mov_b32_dpp v48, v26 row_shr:2 row_mask:0xf bank_mask:0xf bound_ctrl:1
	v_mov_b32_dpp v49, v27 row_shr:2 row_mask:0xf bank_mask:0xf bound_ctrl:1
	v_pk_mul_f32 v[34:35], v[34:35], v[32:33]
	v_mov_b32_dpp v32, v26 row_shr:1 row_mask:0xf bank_mask:0xf bound_ctrl:1
	v_mov_b32_dpp v33, v27 row_shr:1 row_mask:0xf bank_mask:0xf bound_ctrl:1
	v_pk_add_f32 v[46:47], v[48:49], v[46:47]
	v_pk_add_f32 v[32:33], v[32:33], v[50:51]
	v_pk_fma_f32 v[46:47], v[72:73], v[46:47], v[76:77]
	s_nop 0
	v_pk_fma_f32 v[32:33], v[60:61], v[32:33], v[46:47]
	s_nop 0
	v_pk_fma_f32 v[32:33], v[68:69], v[26:27], v[32:33]
	s_nop 0
	v_pk_mul_f32 v[46:47], v[32:33], s[2:3] op_sel_hi:[1,0]
	s_nop 0
	v_exp_f32_e32 v46, v46
	v_exp_f32_e32 v47, v47
	s_nop 0
	v_pk_add_f32 v[46:47], v[46:47], 1.0 op_sel_hi:[1,0]
	s_nop 0
	v_rcp_f32_e32 v46, v46
	v_rcp_f32_e32 v47, v47
	s_nop 0
	v_pk_mul_f32 v[32:33], v[32:33], v[46:47]
	s_nop 0
	v_pk_mul_f32 v[28:29], v[28:29], v[32:33]
	v_cvt_pk_bf16_f32 v32, v36, v37
	v_cvt_pk_bf16_f32 v33, v40, v41
	v_cvt_pk_bf16_f32 v34, v34, v35
	v_cvt_pk_bf16_f32 v35, v28, v29
	v_mad_i64_i32 v[28:29], s[0:1], v52, s93, v[42:43]
	v_lshl_add_u64 v[28:29], v[28:29], 0, v[154:155]
	global_store_dwordx4 v[28:29], v[32:35], off sc1
	ds_read_b32 v28, v223 offset:448
	s_waitcnt lgkmcnt(0)
;     __device__ __forceinline__ void fast(const f32x4 (&acc)[2][2][4][2], const pg8::Unit& u, int wr, int wc, int fr, int fq, RsCache& rsc) const {
;     ...
;                 const int row = rowb + m * 16 + fr; const float s = rsc.tab[ai * 64 + m * 16 + fr]; const f32x2 s2 = (f32x2){s, s};
;                 f32x2 g[4], o[4], v[4];
; #pragma unroll
;                 for (int cp = 0; cp < 4; ++cp) { const int n = cp >> 1, e0 = (cp & 1) * 2;
;                     g[cp] = (f32x2){acc[ai][0][m][n][e0], acc[ai][0][m][n][e0 + 1]} * s2; v[cp] = (f32x2){acc[ai][1][m][n][e0], acc[ai][1][m][n][e0 + 1]} * s2; }
; #pragma unroll
;                 for (int cp = 0; cp < 4; ++cp) {
;                     f32x2 p1 = (f32x2){dppz<0x111>(g[cp].x), dppz<0x111>(g[cp].y)}, p2 = (f32x2){dppz<0x112>(g[cp].x), dppz<0x112>(g[cp].y)};
;                     if (m > 0) { p1 += (f32x2){dppz<0x10F>(gp[cp].x), dppz<0x10F>(gp[cp].y)}; p2 += (f32x2){dppz<0x10E>(gp[cp].x), dppz<0x10E>(gp[cp].y)}; }
;                     const f32x2 gv = bb[cp] + w0[cp] * p2 + w1[cp] * p1 + w2[cp] * g[cp];
;                     const f32x2 ea = gv * (-1.44269504089f);
;                     f32x2 ex; ex.x = __builtin_amdgcn_exp2f(ea.x); ex.y = __builtin_amdgcn_exp2f(ea.y);
;                     const f32x2 dn = ex + 1.0f;
;                     f32x2 rc; rc.x = __builtin_amdgcn_rcpf(dn.x); rc.y = __builtin_amdgcn_rcpf(dn.y);
;                     o[cp] = (gv * rc) * v[cp];
;                 }
;                 if (m > 0 || fr >= 2) { uint4 w; w.x = pk2(o[0].x, o[0].y); w.y = pk2(o[1].x, o[1].y); w.z = pk2(o[2].x, o[2].y); w.w = pk2(o[3].x, o[3].y); *(uint4*)(act + (size_t)row * FH + ch) = w; }
;                 if (m == 0 && fr < 2) { uint4 w; w.x = pk2(g[0].x, g[0].y); w.y = pk2(g[1].x, g[1].y); w.z = pk2(g[2].x, g[2].y); w.w = pk2(g[3].x, g[3].y); *(uint4*)(sideg + ((size_t)blk * 4 + fr) * FH + ch) = w;
;                     uint4 q; q.x = pk2(v[0].x, v[0].y); q.y = pk2(v[1].x, v[1].y); q.z = pk2(v[2].x, v[2].y); q.w = pk2(v[3].x, v[3].y); *(uint4*)(sidev + ((size_t)blk * 2 + fr) * FH + ch) = q; }
;                 if (m == 3 && fr >= 14) { uint4 w; w.x = pk2(g[0].x, g[0].y); w.y = pk2(g[1].x, g[1].y); w.z = pk2(g[2].x, g[2].y); w.w = pk2(g[3].x, g[3].y); *(uint4*)(sideg + ((size_t)blk * 4 + 2 + (fr - 14)) * FH + ch) = w; }
	v_pk_mul_f32 v[22:23], v[22:23], v[28:29] op_sel_hi:[1,0]
	v_pk_mul_f32 v[32:33], v[14:15], v[28:29] op_sel_hi:[1,0]
	v_pk_mul_f32 v[14:15], v[24:25], v[28:29] op_sel_hi:[1,0]
	v_pk_mul_f32 v[24:25], v[16:17], v[28:29] op_sel_hi:[1,0]
	v_pk_mul_f32 v[16:17], v[18:19], v[28:29] op_sel_hi:[1,0]
	v_pk_mul_f32 v[18:19], v[10:11], v[28:29] op_sel_hi:[1,0]
	v_pk_mul_f32 v[10:11], v[20:21], v[28:29] op_sel_hi:[1,0]
	v_pk_mul_f32 v[12:13], v[12:13], v[28:29] op_sel_hi:[1,0]
	v_mov_b32_dpp v28, v22 row_shr:2 row_mask:0xf bank_mask:0xf bound_ctrl:1
	v_mov_b32_dpp v29, v23 row_shr:2 row_mask:0xf bank_mask:0xf bound_ctrl:1
	v_mov_b32_dpp v20, v22 row_shr:1 row_mask:0xf bank_mask:0xf bound_ctrl:1
	v_mov_b32_dpp v21, v23 row_shr:1 row_mask:0xf bank_mask:0xf bound_ctrl:1
	v_mov_b32_dpp v28, v44 row_shl:14 row_mask:0xf bank_mask:0xf
	v_mov_b32_dpp v29, v45 row_shl:14 row_mask:0xf bank_mask:0xf
	v_mov_b32_dpp v20, v44 row_shl:15 row_mask:0xf bank_mask:0xf
	v_mov_b32_dpp v21, v45 row_shl:15 row_mask:0xf bank_mask:0xf
	v_pk_fma_f32 v[28:29], v[90:91], v[28:29], v[102:103]
	v_pk_fma_f32 v[20:21], v[94:95], v[20:21], v[28:29]
	v_pk_fma_f32 v[20:21], v[98:99], v[22:23], v[20:21]
	v_pk_mul_f32 v[28:29], v[20:21], s[2:3] op_sel_hi:[1,0]
	v_exp_f32_e32 v28, v28
	v_exp_f32_e32 v29, v29
	s_nop 0
	v_pk_add_f32 v[28:29], v[28:29], 1.0 op_sel_hi:[1,0]
	s_nop 0
	v_rcp_f32_e32 v28, v28
	v_rcp_f32_e32 v29, v29
	s_nop 0
	v_pk_mul_f32 v[20:21], v[20:21], v[28:29]
	s_nop 0
	v_pk_mul_f32 v[20:21], v[32:33], v[20:21]
	v_mov_b32_dpp v32, v14 row_shr:2 row_mask:0xf bank_mask:0xf bound_ctrl:1
	v_mov_b32_dpp v33, v15 row_shr:2 row_mask:0xf bank_mask:0xf bound_ctrl:1
	v_mov_b32_dpp v28, v14 row_shr:1 row_mask:0xf bank_mask:0xf bound_ctrl:1
	v_mov_b32_dpp v29, v15 row_shr:1 row_mask:0xf bank_mask:0xf bound_ctrl:1
	v_mov_b32_dpp v32, v38 row_shl:14 row_mask:0xf bank_mask:0xf
	v_mov_b32_dpp v33, v39 row_shl:14 row_mask:0xf bank_mask:0xf
	v_mov_b32_dpp v28, v38 row_shl:15 row_mask:0xf bank_mask:0xf
	v_mov_b32_dpp v29, v39 row_shl:15 row_mask:0xf bank_mask:0xf
	v_pk_fma_f32 v[32:33], v[92:93], v[32:33], v[104:105]
	v_mov_b32_dpp v34, v30 row_shl:15 row_mask:0xf bank_mask:0xf bound_ctrl:1
	v_pk_fma_f32 v[28:29], v[96:97], v[28:29], v[32:33]
	v_mov_b32_dpp v35, v31 row_shl:15 row_mask:0xf bank_mask:0xf bound_ctrl:1
	v_pk_fma_f32 v[28:29], v[100:101], v[14:15], v[28:29]
	v_mov_b32_dpp v30, v30 row_shl:14 row_mask:0xf bank_mask:0xf bound_ctrl:1
	v_pk_mul_f32 v[32:33], v[28:29], s[2:3] op_sel_hi:[1,0]
	v_mov_b32_dpp v31, v31 row_shl:14 row_mask:0xf bank_mask:0xf bound_ctrl:1
	v_exp_f32_e32 v32, v32
	v_exp_f32_e32 v33, v33
	s_nop 0
	v_pk_add_f32 v[32:33], v[32:33], 1.0 op_sel_hi:[1,0]
	s_nop 0
	v_rcp_f32_e32 v32, v32
	v_rcp_f32_e32 v33, v33
	s_nop 0
	v_pk_mul_f32 v[28:29], v[28:29], v[32:33]
	v_mov_b32_dpp v32, v16 row_shr:2 row_mask:0xf bank_mask:0xf bound_ctrl:1
	v_mov_b32_dpp v33, v17 row_shr:2 row_mask:0xf bank_mask:0xf bound_ctrl:1
	v_pk_mul_f32 v[24:25], v[24:25], v[28:29]
	v_mov_b32_dpp v28, v16 row_shr:1 row_mask:0xf bank_mask:0xf bound_ctrl:1
	v_mov_b32_dpp v29, v17 row_shr:1 row_mask:0xf bank_mask:0xf bound_ctrl:1
	v_pk_add_f32 v[30:31], v[32:33], v[30:31]
	v_pk_add_f32 v[28:29], v[28:29], v[34:35]
	v_pk_fma_f32 v[30:31], v[70:71], v[30:31], v[74:75]
	v_mov_b32_dpp v32, v26 row_shl:15 row_mask:0xf bank_mask:0xf bound_ctrl:1
	v_pk_fma_f32 v[28:29], v[58:59], v[28:29], v[30:31]
	v_mov_b32_dpp v33, v27 row_shl:15 row_mask:0xf bank_mask:0xf bound_ctrl:1
	v_pk_fma_f32 v[28:29], v[66:67], v[16:17], v[28:29]
	v_mov_b32_dpp v26, v26 row_shl:14 row_mask:0xf bank_mask:0xf bound_ctrl:1
	v_pk_mul_f32 v[30:31], v[28:29], s[2:3] op_sel_hi:[1,0]
	v_mov_b32_dpp v27, v27 row_shl:14 row_mask:0xf bank_mask:0xf bound_ctrl:1
	v_exp_f32_e32 v30, v30
	v_exp_f32_e32 v31, v31
	v_add_u32_e32 v34, 48, v122
	v_pk_add_f32 v[30:31], v[30:31], 1.0 op_sel_hi:[1,0]
	s_nop 0
	v_rcp_f32_e32 v30, v30
	v_rcp_f32_e32 v31, v31
	s_nop 0
	v_pk_mul_f32 v[28:29], v[28:29], v[30:31]
	v_mov_b32_dpp v30, v10 row_shr:2 row_mask:0xf bank_mask:0xf bound_ctrl:1
	v_mov_b32_dpp v31, v11 row_shr:2 row_mask:0xf bank_mask:0xf bound_ctrl:1
	v_pk_mul_f32 v[28:29], v[18:19], v[28:29]
	v_mov_b32_dpp v18, v10 row_shr:1 row_mask:0xf bank_mask:0xf bound_ctrl:1
	v_mov_b32_dpp v19, v11 row_shr:1 row_mask:0xf bank_mask:0xf bound_ctrl:1
	v_pk_add_f32 v[26:27], v[30:31], v[26:27]
	v_pk_add_f32 v[18:19], v[18:19], v[32:33]
	v_pk_fma_f32 v[26:27], v[72:73], v[26:27], v[76:77]
	s_nop 0
	v_pk_fma_f32 v[18:19], v[60:61], v[18:19], v[26:27]
	s_nop 0
	v_pk_fma_f32 v[18:19], v[68:69], v[10:11], v[18:19]
	s_nop 0
	v_pk_mul_f32 v[26:27], v[18:19], s[2:3] op_sel_hi:[1,0]
	s_nop 0
	v_exp_f32_e32 v26, v26
	v_exp_f32_e32 v27, v27
	s_nop 0
	v_pk_add_f32 v[26:27], v[26:27], 1.0 op_sel_hi:[1,0]
	s_nop 0
	v_rcp_f32_e32 v26, v26
	v_rcp_f32_e32 v27, v27
	s_nop 0
	v_pk_mul_f32 v[18:19], v[18:19], v[26:27]
	s_nop 0
	v_pk_mul_f32 v[12:13], v[12:13], v[18:19]
	v_cvt_pk_bf16_f32 v18, v20, v21
	v_cvt_pk_bf16_f32 v19, v24, v25
	v_cvt_pk_bf16_f32 v20, v28, v29
	s_nop 0
	v_cvt_pk_bf16_f32 v21, v12, v13
	v_mad_i64_i32 v[12:13], s[0:1], v34, s93, v[42:43]
	v_lshl_add_u64 v[12:13], v[12:13], 0, v[154:155]
	global_store_dwordx4 v[12:13], v[18:21], off sc1
	s_and_saveexec_b64 s[0:1], vcc
	s_cbranch_execz .LBB0_278
	v_readlane_b32 s2, v254, 1
	v_readlane_b32 s3, v254, 2
	v_lshl_add_u64 v[18:19], s[6:7], 0, v[156:157]
	v_cvt_pk_bf16_f32 v12, v22, v23
	v_cvt_pk_bf16_f32 v13, v14, v15
	v_cvt_pk_bf16_f32 v14, v16, v17
	v_cvt_pk_bf16_f32 v15, v10, v11
	s_nop 0
	v_mov_b64_e32 v[10:11], s[2:3]
	v_mad_u64_u32 v[10:11], s[2:3], v18, s93, v[10:11]
	v_mad_i32_i24 v11, v19, s93, v11
	v_lshl_add_u64 v[10:11], v[184:185], 1, v[10:11]
	global_store_dwordx4 v[10:11], v[12:15], off sc1
